# GEMM mainloops: per-phase priority flips deleted, one static priority raise for waves 0-3
# speedup vs baseline: 1.0055x; 1.0055x over previous
.LBB0_278:
	s_or_b64 exec, exec, s[10:11]
	v_bfe_i32 v3, v234, 27, 1
	v_lshlrev_b32_e32 v6, 4, v234
	v_lshrrev_b32_e32 v3, 22, v3
	v_ashrrev_i32_e32 v2, 31, v234
	v_add_u32_e32 v3, v6, v3
	v_lshrrev_b32_e32 v2, 26, v2
	v_and_b32_e32 v3, 0xfffffc00, v3
	s_sub_i32 s9, 2, s29
	v_add_u32_e32 v2, v234, v2
	v_sub_u32_e32 v3, v6, v3
	s_mul_hi_i32 s10, s9, 0x600000
	s_mul_i32 s9, s9, 0x600000
	v_ashrrev_i32_e32 v2, 6, v2
	v_lshrrev_b32_e32 v4, 4, v3
	s_add_u32 s9, s0, s9
	v_bitop3_b32 v4, v4, v3, 32 bitop3:0x6c
	v_lshlrev_b32_e32 v3, 3, v2
	s_addc_u32 s10, s1, s10
	v_and_b32_e32 v7, -16, v3
	v_ashrrev_i32_e32 v3, 31, v4
	s_add_u32 s40, s9, 0x500000
	v_lshrrev_b32_e32 v3, 26, v3
	s_addc_u32 s41, s10, 0
	s_ashr_i32 s9, s8, 31
	v_add_u32_e32 v8, v4, v3
	s_lshl_b64 s[10:11], s[8:9], 19
	v_ashrrev_i32_e32 v3, 6, v8
	v_and_b32_e32 v8, 0xc0, v8
	s_add_u32 s28, s80, s10
	v_sub_u32_e32 v4, v4, v8
	s_addc_u32 s29, s81, s11
	s_ashr_i32 s27, s26, 31
	v_lshlrev_b32_e32 v9, 5, v2
	v_ashrrev_i16_sdwa v4, v226, sext(v4) dst_sel:DWORD dst_unused:UNUSED_PAD src0_sel:DWORD src1_sel:BYTE_0
	s_lshl_b64 s[10:11], s[26:27], 19
	v_and_b32_e32 v9, 32, v9
	v_bfe_i32 v4, v4, 0, 16
	s_add_u32 s30, s40, s10
	v_add_u32_e32 v7, v3, v7
	v_and_b32_e32 v11, 3, v3
	s_mov_b32 s10, 0x1fffe0
	v_add_lshl_u32 v9, v9, v4, 1
	v_lshlrev_b32_e32 v8, 1, v7
	v_lshrrev_b32_e32 v10, 2, v7
	v_and_or_b32 v11, v7, s10, v11
	v_lshl_add_u32 v130, v7, 11, v9
	v_add_u32_e32 v7, 0x2000, v6
	v_ashrrev_i32_e32 v6, 31, v7
	v_lshrrev_b32_e32 v6, 22, v6
	v_and_b32_e32 v8, 24, v8
	v_and_b32_e32 v10, 4, v10
	v_add_u32_e32 v6, v7, v6
	v_or3_b32 v8, v11, v10, v8
	v_ashrrev_i32_e32 v6, 10, v6
	v_lshl_add_u32 v132, v8, 11, v9
	v_mul_i32_i24_e32 v8, 0x400, v6
	v_sub_u32_e32 v7, v7, v8
	v_lshrrev_b32_e32 v8, 4, v7
	v_bitop3_b32 v8, v8, v7, 32 bitop3:0x6c
	v_lshlrev_b32_e32 v7, 3, v6
	v_and_b32_e32 v9, -16, v7
	v_ashrrev_i32_e32 v7, 31, v8
	v_lshrrev_b32_e32 v7, 26, v7
	v_add_u32_e32 v10, v8, v7
	s_addc_u32 s31, s41, s11
	s_ashr_i32 s9, s14, 6
	v_ashrrev_i32_e32 v7, 6, v10
	v_and_b32_e32 v10, 0xc0, v10
	v_add_u32_e32 v9, v7, v9
	v_sub_u32_e32 v8, v8, v10
	s_lshl_b32 s27, s9, 10
	v_lshlrev_b32_e32 v11, 5, v6
	v_ashrrev_i16_sdwa v8, v226, sext(v8) dst_sel:DWORD dst_unused:UNUSED_PAD src0_sel:DWORD src1_sel:BYTE_0
	v_lshlrev_b32_e32 v10, 1, v9
	v_lshrrev_b32_e32 v12, 2, v9
	v_and_b32_e32 v13, 3, v7
	s_add_i32 s44, s27, 0
	v_and_b32_e32 v11, 32, v11
	v_bfe_i32 v8, v8, 0, 16
	v_and_b32_e32 v10, 24, v10
	v_and_b32_e32 v12, 4, v12
	v_and_or_b32 v13, v9, s10, v13
	s_add_i32 m0, s44, 0x10000
	v_or3_b32 v10, v13, v12, v10
	v_add_lshl_u32 v11, v11, v8, 1
	s_ashr_i32 s16, s14, 8
	global_load_lds_dwordx4 v132, s[30:31]
	s_add_i32 m0, s44, 0x12000
	v_lshl_add_u32 v136, v10, 11, v11
	s_add_u32 s10, s30, 0x40000
	global_load_lds_dwordx4 v136, s[30:31]
	s_addc_u32 s11, s31, 0
	s_add_i32 m0, s44, 0x14000
	s_add_i32 s45, s44, 0x2000
	global_load_lds_dwordx4 v132, s[10:11]
	s_add_i32 m0, s44, 0x16000
	v_lshl_add_u32 v134, v9, 11, v11
	global_load_lds_dwordx4 v136, s[10:11]
	s_mov_b32 m0, s44
	s_add_u32 s10, s28, 0x40000
	global_load_lds_dwordx4 v130, s[28:29]
	s_mov_b32 m0, s45
	s_addc_u32 s11, s29, 0
	s_add_i32 s43, s44, 0x4000
	global_load_lds_dwordx4 v134, s[28:29]
	s_mov_b32 m0, s43
	s_add_i32 s46, s44, 0x6000
	global_load_lds_dwordx4 v130, s[10:11]
	s_mov_b32 m0, s46
	s_cmp_eq_u32 s16, 1
	global_load_lds_dwordx4 v134, s[10:11]
	s_cselect_b64 s[10:11], -1, 0
	s_cmp_lg_u32 s16, 1
	s_cbranch_scc1 .Lprio0_0
	s_barrier
	s_branch .LBB0_280
.Lprio0_0:
	s_setprio 1

.LBB0_354:
	v_readlane_b32 s6, v254, 47
	s_cmpk_gt_i32 s6, 0x57f
	v_readfirstlane_b32 s16, v234
	v_readlane_b32 s7, v254, 48
	s_cbranch_scc1 .LBB0_386
	v_lshlrev_b32_e32 v2, 4, v234
	v_add_u32_e32 v3, 0x2000, v2
	v_ashrrev_i32_e32 v4, 31, v3
	v_lshrrev_b32_e32 v4, 22, v4
	v_add_u32_e32 v4, v3, v4
	v_ashrrev_i32_e32 v10, 10, v4
	v_mul_i32_i24_e32 v4, 0x400, v10
	v_sub_u32_e32 v3, v3, v4
	v_lshrrev_b32_e32 v4, 4, v3
	v_bitop3_b32 v3, v4, v3, 32 bitop3:0x6c
	s_ashr_i32 s17, s16, 6
	v_ashrrev_i32_e32 v4, 31, v3
	s_ashr_i32 s18, s16, 8
	s_lshl_b32 s44, s17, 10
	v_lshrrev_b32_e32 v4, 26, v4
	s_and_b64 s[6:7], s[4:5], exec
	v_add_u32_e32 v4, v3, v4
	v_lshlrev_b32_e32 v5, 3, v10
	s_mov_b32 s6, 0x1900000
	v_ashrrev_i32_e32 v12, 6, v4
	v_and_b32_e32 v5, -16, v5
	s_cselect_b32 s6, s6, 0x5180000
	v_add_u32_e32 v5, v12, v5
	s_add_u32 s45, s0, s6
	v_and_b32_e32 v6, 3, v12
	s_mov_b32 s6, 0x1fffe0
	v_lshrrev_b32_e32 v7, 2, v5
	v_lshlrev_b32_e32 v8, 1, v5
	v_and_b32_e32 v4, 0xc0, v4
	v_and_or_b32 v6, v5, s6, v6
	v_and_b32_e32 v7, 4, v7
	v_and_b32_e32 v8, 24, v8
	v_sub_u32_e32 v3, v3, v4
	v_or3_b32 v6, v6, v7, v8
	v_lshlrev_b32_e32 v7, 5, v10
	v_ashrrev_i16_sdwa v3, v226, sext(v3) dst_sel:DWORD dst_unused:UNUSED_PAD src0_sel:DWORD src1_sel:BYTE_0
	v_and_b32_e32 v7, 32, v7
	v_bfe_i32 v13, v3, 0, 16
	v_add_lshl_u32 v3, v7, v13, 1
	s_waitcnt vmcnt(0)
	v_lshl_add_u32 v130, v6, 11, v3
	v_lshl_add_u32 v132, v5, 11, v3
	v_bfe_i32 v3, v234, 27, 1
	v_lshrrev_b32_e32 v3, 22, v3
	v_add_u32_e32 v3, v2, v3
	v_and_b32_e32 v3, 0xfffffc00, v3
	v_sub_u32_e32 v2, v2, v3
	v_lshrrev_b32_e32 v3, 4, v2
	v_ashrrev_i32_e32 v4, 31, v234
	s_addc_u32 s46, s1, 0
	v_bitop3_b32 v2, v3, v2, 32 bitop3:0x6c
	v_lshrrev_b32_e32 v4, 26, v4
	v_ashrrev_i32_e32 v3, 31, v2
	v_add_u32_e32 v4, v234, v4
	s_and_b64 s[4:5], s[4:5], exec
	v_lshrrev_b32_e32 v3, 26, v3
	v_ashrrev_i32_e32 v15, 6, v4
	s_mov_b32 s4, 0x30000
	v_add_u32_e32 v3, v2, v3
	v_lshlrev_b32_e32 v4, 3, v15
	s_cselect_b32 s4, s4, 0x10000
	v_ashrrev_i32_e32 v14, 6, v3
	v_and_b32_e32 v4, -16, v4
	s_add_u32 s12, s78, s4
	v_readlane_b32 s4, v254, 47
	v_add_u32_e32 v4, v14, v4
	v_and_b32_e32 v5, 3, v14
	s_addc_u32 s13, s79, 0
	s_ashr_i32 s47, s4, 31
	v_and_or_b32 v5, v4, s6, v5
	s_mov_b32 s6, s4
	s_lshr_b32 s4, s47, 29
	v_readlane_b32 s5, v254, 48
	s_add_i32 s4, s6, s4
	s_ashr_i32 s5, s4, 3
	s_and_b32 s4, s4, -8
	s_sub_i32 s4, s6, s4
	s_cmp_lt_i32 s4, 0
	s_movk_i32 s6, 0xb1
	s_cselect_b32 s6, s6, 0xb0
	s_mul_i32 s4, s4, s6
	s_add_i32 s4, s4, s5
	s_mul_hi_i32 s5, s4, 0x2e8ba2e9
	s_lshr_b32 s6, s5, 31
	s_ashr_i32 s5, s5, 5
	s_add_i32 s5, s5, s6
	s_lshl_b32 s6, s5, 3
	s_mulk_i32 s5, 0xb0
	s_sub_i32 s5, s4, s5
	s_bfe_u32 s4, s5, 0x3001c
	s_add_i32 s7, s5, s4
	s_sext_i32_i16 s4, s7
	s_and_b32 s7, s7, 0xfff8
	s_sub_i32 s5, s5, s7
	s_sext_i32_i16 s5, s5
	v_lshrrev_b32_e32 v6, 2, v4
	v_lshlrev_b32_e32 v7, 1, v4
	v_and_b32_e32 v3, 0xc0, v3
	s_lshr_b32 s4, s4, 3
	s_add_i32 s28, s6, s5
	v_and_b32_e32 v6, 4, v6
	v_and_b32_e32 v7, 24, v7
	v_sub_u32_e32 v2, v2, v3
	s_ashr_i32 s29, s28, 31
	s_bfe_i64 s[14:15], s[4:5], 0x100000
	v_or3_b32 v5, v5, v6, v7
	v_lshlrev_b32_e32 v6, 5, v15
	v_ashrrev_i16_sdwa v2, v226, sext(v2) dst_sel:DWORD dst_unused:UNUSED_PAD src0_sel:DWORD src1_sel:BYTE_0
	s_lshl_b64 s[6:7], s[28:29], 19
	s_lshl_b64 s[14:15], s[14:15], 19
	v_and_b32_e32 v11, 15, v233
	v_and_b32_e32 v6, 32, v6
	v_bfe_i32 v16, v2, 0, 16
	s_add_u32 s30, s45, s14
	v_lshl_or_b32 v1, s18, 6, v11
	v_add_lshl_u32 v2, v6, v16, 1
	s_addc_u32 s31, s46, s15
	s_lshl_b32 s5, s28, 8
	v_lshl_add_u32 v134, v5, 11, v2
	v_lshl_add_u32 v136, v4, 11, v2
	v_add_u32_e32 v2, s5, v1
	v_ashrrev_i32_e32 v3, 31, v2
	v_lshl_add_u64 v[2:3], v[2:3], 2, s[12:13]
	v_or_b32_e32 v148, 16, v1
	global_load_dword v166, v[2:3], off
	v_add_u32_e32 v2, s5, v148
	v_ashrrev_i32_e32 v3, 31, v2
	v_lshl_add_u64 v[2:3], v[2:3], 2, s[12:13]
	v_or_b32_e32 v149, 32, v1
	global_load_dword v165, v[2:3], off
	v_add_u32_e32 v2, s5, v149
	v_ashrrev_i32_e32 v3, 31, v2
	v_lshl_add_u64 v[2:3], v[2:3], 2, s[12:13]
	v_or_b32_e32 v150, 48, v1
	global_load_dword v163, v[2:3], off
	v_add_u32_e32 v2, s5, v150
	v_ashrrev_i32_e32 v3, 31, v2
	v_lshl_add_u64 v[2:3], v[2:3], 2, s[12:13]
	v_add_u32_e32 v151, 0x80, v1
	global_load_dword v162, v[2:3], off
	v_add_u32_e32 v2, s5, v151
	v_ashrrev_i32_e32 v3, 31, v2
	s_add_i32 s48, s44, 0
	v_lshl_add_u64 v[2:3], v[2:3], 2, s[12:13]
	v_add_u32_e32 v152, 0x90, v1
	s_add_i32 m0, s48, 0x10000
	global_load_dword v161, v[2:3], off
	v_add_u32_e32 v2, s5, v152
	global_load_lds_dwordx4 v134, s[30:31]
	s_add_i32 m0, s48, 0x12000
	v_ashrrev_i32_e32 v3, 31, v2
	s_add_u32 s14, s30, 0x40000
	v_lshl_add_u64 v[2:3], v[2:3], 2, s[12:13]
	v_add_u32_e32 v153, 0xa0, v1
	global_load_lds_dwordx4 v130, s[30:31]
	s_addc_u32 s15, s31, 0
	s_add_i32 m0, s48, 0x14000
	global_load_dword v160, v[2:3], off
	v_add_u32_e32 v2, s5, v153
	global_load_lds_dwordx4 v134, s[14:15]
	s_add_i32 m0, s48, 0x16000
	v_ashrrev_i32_e32 v3, 31, v2
	s_add_u32 s34, s80, s6
	v_lshl_add_u64 v[2:3], v[2:3], 2, s[12:13]
	v_add_u32_e32 v154, 0xb0, v1
	s_addc_u32 s35, s81, s7
	s_add_i32 s49, s48, 0x2000
	global_load_dword v159, v[2:3], off
	v_add_u32_e32 v2, s5, v154
	global_load_lds_dwordx4 v130, s[14:15]
	s_mov_b32 m0, s48
	s_add_u32 s6, s34, 0x40000
	v_ashrrev_i32_e32 v3, 31, v2
	global_load_lds_dwordx4 v136, s[34:35]
	s_mov_b32 m0, s49
	s_addc_u32 s7, s35, 0
	s_add_i32 s50, s48, 0x4000
	v_lshl_add_u64 v[2:3], v[2:3], 2, s[12:13]
	global_load_lds_dwordx4 v132, s[34:35]
	s_mov_b32 m0, s50
	s_add_i32 s51, s48, 0x6000
	global_load_dword v158, v[2:3], off
	v_mov_b32_e32 v135, v0
	global_load_lds_dwordx4 v136, s[6:7]
	s_mov_b32 m0, s51
	v_mov_b32_e32 v131, v0
	global_load_lds_dwordx4 v132, s[6:7]
	v_mov_b32_e32 v137, v0
	v_mov_b32_e32 v133, v0
	s_cmp_eq_u32 s18, 1
	v_lshl_add_u64 v[2:3], s[30:31], 0, v[134:135]
	v_lshl_add_u64 v[4:5], s[30:31], 0, v[130:131]
	v_lshl_add_u64 v[6:7], s[34:35], 0, v[136:137]
	v_lshl_add_u64 v[8:9], s[34:35], 0, v[132:133]
	s_cselect_b64 s[14:15], -1, 0
	s_cmp_lg_u32 s18, 1
	s_cbranch_scc1 .Lprio0_1
	s_barrier
	s_branch .LBB0_357

.LBB0_461:
	v_bfe_i32 v3, v234, 27, 1
	v_lshlrev_b32_e32 v1, 4, v234
	v_lshrrev_b32_e32 v3, 22, v3
	v_add_u32_e32 v3, v1, v3
	v_and_b32_e32 v3, 0xfffffc00, v3
	v_sub_u32_e32 v3, v1, v3
	s_ashr_i32 s8, s6, 3
	v_ashrrev_i32_e32 v2, 31, v234
	v_lshrrev_b32_e32 v4, 4, v3
	s_cmp_lg_u32 s74, 14
	v_lshrrev_b32_e32 v2, 26, v2
	v_bitop3_b32 v3, v4, v3, 32 bitop3:0x6c
	s_cselect_b64 s[14:15], -1, 0
	s_cmp_eq_u32 s74, 14
	v_add_u32_e32 v2, v234, v2
	v_ashrrev_i32_e32 v5, 31, v3
	s_cselect_b64 s[4:5], -1, 0
	v_ashrrev_i32_e32 v2, 6, v2
	v_lshrrev_b32_e32 v5, 26, v5
	s_or_b64 s[4:5], s[20:21], s[4:5]
	v_lshlrev_b32_e32 v4, 3, v2
	v_add_u32_e32 v5, v3, v5
	s_and_b64 s[4:5], s[4:5], exec
	v_and_b32_e32 v4, -16, v4
	v_ashrrev_i32_e32 v6, 6, v5
	s_movk_i32 s4, 0xb00
	v_add_u32_e32 v4, v6, v4
	v_and_b32_e32 v5, 0xc0, v5
	s_cselect_b32 s6, s4, 0x400
	v_sub_u32_e32 v3, v3, v5
	v_lshlrev_b32_e32 v7, 1, v4
	v_lshrrev_b32_e32 v8, 2, v4
	v_and_b32_e32 v6, 3, v6
	s_mov_b32 s4, 0xffffe0
	v_lshlrev_b32_e32 v2, 5, v2
	v_ashrrev_i16_sdwa v3, v226, sext(v3) dst_sel:DWORD dst_unused:UNUSED_PAD src0_sel:DWORD src1_sel:BYTE_0
	v_and_b32_e32 v7, 24, v7
	v_and_b32_e32 v8, 4, v8
	v_and_or_b32 v6, v4, s4, v6
	v_and_b32_e32 v2, 32, v2
	v_bfe_i32 v3, v3, 0, 16
	v_or3_b32 v6, v6, v8, v7
	v_add_u32_e32 v5, v2, v3
	v_mul_lo_u32 v4, v4, s6
	v_mul_u32_u24_e32 v6, s6, v6
	v_add_u32_e32 v1, 0x2000, v1
	s_waitcnt vmcnt(0)
	v_add_lshl_u32 v130, v5, v4, 1
	v_add_lshl_u32 v132, v6, v5, 1
	v_ashrrev_i32_e32 v5, 31, v1
	v_lshrrev_b32_e32 v5, 22, v5
	v_add_u32_e32 v5, v1, v5
	v_ashrrev_i32_e32 v5, 10, v5
	v_mul_i32_i24_e32 v6, 0x400, v5
	v_sub_u32_e32 v1, v1, v6
	v_lshrrev_b32_e32 v6, 4, v1
	v_bitop3_b32 v1, v6, v1, 32 bitop3:0x6c
	v_ashrrev_i32_e32 v7, 31, v1
	v_lshrrev_b32_e32 v7, 26, v7
	v_lshlrev_b32_e32 v6, 3, v5
	v_add_u32_e32 v7, v1, v7
	s_ashr_i32 s13, s43, 6
	v_and_b32_e32 v6, -16, v6
	v_ashrrev_i32_e32 v8, 6, v7
	s_ashr_i32 s40, s43, 8
	v_add_u32_e32 v9, v8, v6
	v_and_b32_e32 v8, 3, v8
	s_lshl_b32 s45, s6, 8
	s_lshl_b32 s46, s6, 9
	s_lshl_b32 s47, s13, 10
	v_and_or_b32 v8, v9, s4, v8
	s_and_b64 s[4:5], s[20:21], exec
	s_mov_b32 s4, 0x5c80000
	s_cselect_b32 s9, s4, 0x2400000
	s_and_b64 s[4:5], s[16:17], exec
	s_cselect_b32 s9, 0x1700000, s9
	s_and_b64 s[4:5], exec, s[18:19]
	s_cselect_b32 s4, 0x4f80000, s9
	s_add_u32 s48, s0, s4
	s_addc_u32 s49, s1, 0
	s_add_i32 s4, s7, s8
	s_ashr_i32 s5, s4, 31
	s_lshr_b32 s5, s5, 27
	s_add_i32 s5, s4, s5
	s_ashr_i32 s7, s5, 5
	s_and_b32 s5, s5, 0xffe0
	s_sub_i32 s4, s4, s5
	s_bfe_i32 s5, s4, 0x80000
	s_bfe_u32 s5, s5, 0x3000c
	s_add_i32 s5, s4, s5
	s_lshl_b32 s8, s7, 3
	s_bfe_i32 s7, s5, 0x80000
	s_and_b32 s5, s5, 0xf8
	s_sub_i32 s4, s4, s5
	s_sext_i32_i16 s7, s7
	s_sext_i32_i8 s4, s4
	s_add_i32 s50, s8, s4
	s_ashr_i32 s4, s7, 3
	v_and_b32_e32 v6, 0xc0, v7
	s_mul_hi_i32 s5, s46, s4
	s_mul_i32 s4, s46, s4
	v_sub_u32_e32 v1, v1, v6
	v_lshlrev_b32_e32 v7, 1, v9
	v_lshrrev_b32_e32 v10, 2, v9
	s_add_u32 s26, s48, s4
	v_lshlrev_b32_e32 v5, 5, v5
	v_ashrrev_i16_sdwa v1, v226, sext(v1) dst_sel:DWORD dst_unused:UNUSED_PAD src0_sel:DWORD src1_sel:BYTE_0
	v_and_b32_e32 v7, 24, v7
	v_and_b32_e32 v10, 4, v10
	s_addc_u32 s27, s49, s5
	s_add_i32 s51, s47, 0
	v_and_b32_e32 v5, 32, v5
	v_bfe_i32 v6, v1, 0, 16
	v_or3_b32 v8, v8, v10, v7
	s_add_i32 m0, s51, 0x10000
	v_add_u32_e32 v1, v5, v6
	v_mul_u32_u24_e32 v8, s6, v8
	global_load_lds_dwordx4 v132, s[26:27]
	s_add_i32 m0, s51, 0x12000
	v_add_lshl_u32 v136, v8, v1, 1
	s_add_u32 s4, s26, s45
	global_load_lds_dwordx4 v136, s[26:27]
	s_addc_u32 s5, s27, 0
	s_add_i32 m0, s51, 0x14000
	s_mul_i32 s9, s46, s50
	global_load_lds_dwordx4 v132, s[4:5]
	s_add_i32 m0, s51, 0x16000
	s_mul_hi_i32 s8, s46, s50
	s_add_u32 s28, s22, s9
	s_addc_u32 s29, s23, s8
	s_add_i32 s52, s51, 0x2000
	v_mul_lo_u32 v7, v9, s6
	global_load_lds_dwordx4 v136, s[4:5]
	s_mov_b32 m0, s51
	s_add_u32 s8, s28, s45
	v_add_lshl_u32 v134, v1, v7, 1
	global_load_lds_dwordx4 v130, s[28:29]
	s_mov_b32 m0, s52
	s_addc_u32 s9, s29, 0
	s_add_i32 s53, s51, 0x4000
	global_load_lds_dwordx4 v134, s[28:29]
	s_mov_b32 m0, s53
	s_add_i32 s54, s51, 0x6000
	global_load_lds_dwordx4 v130, s[8:9]
	s_mov_b32 m0, s54
	s_cmp_lg_u32 s40, 1
	global_load_lds_dwordx4 v134, s[8:9]
	s_cbranch_scc1 .Lprio0_2
	s_barrier
	s_branch .LBB0_463

.LBB0_631:
	s_cmpk_gt_i32 s52, 0x2ff
	v_readfirstlane_b32 s5, v234
	s_cbranch_scc1 .LBB0_651
	v_lshlrev_b32_e32 v2, 4, v234
	s_waitcnt lgkmcnt(0)
	v_add_u32_e32 v3, 0x2000, v2
	v_ashrrev_i32_e32 v4, 31, v3
	v_lshrrev_b32_e32 v4, 22, v4
	v_add_u32_e32 v4, v3, v4
	v_ashrrev_i32_e32 v10, 10, v4
	v_mul_i32_i24_e32 v4, 0x400, v10
	v_sub_u32_e32 v3, v3, v4
	v_lshrrev_b32_e32 v4, 4, v3
	v_bitop3_b32 v3, v4, v3, 32 bitop3:0x6c
	v_ashrrev_i32_e32 v4, 31, v3
	v_lshrrev_b32_e32 v4, 26, v4
	v_add_u32_e32 v4, v3, v4
	v_lshlrev_b32_e32 v5, 3, v10
	v_ashrrev_i32_e32 v12, 6, v4
	v_and_b32_e32 v5, -16, v5
	v_add_u32_e32 v5, v12, v5
	v_and_b32_e32 v6, 3, v12
	s_mov_b32 s4, 0x1fffe0
	v_lshrrev_b32_e32 v7, 2, v5
	v_lshlrev_b32_e32 v8, 1, v5
	v_and_b32_e32 v4, 0xc0, v4
	v_and_or_b32 v6, v5, s4, v6
	v_and_b32_e32 v7, 4, v7
	v_and_b32_e32 v8, 24, v8
	v_sub_u32_e32 v3, v3, v4
	v_or3_b32 v6, v6, v7, v8
	v_lshlrev_b32_e32 v7, 5, v10
	v_ashrrev_i16_sdwa v3, v226, sext(v3) dst_sel:DWORD dst_unused:UNUSED_PAD src0_sel:DWORD src1_sel:BYTE_0
	v_and_b32_e32 v7, 32, v7
	v_bfe_i32 v13, v3, 0, 16
	v_add_lshl_u32 v3, v7, v13, 1
	s_waitcnt vmcnt(0)
	v_lshl_add_u32 v130, v6, 11, v3
	v_lshl_add_u32 v132, v5, 11, v3
	v_bfe_i32 v3, v234, 27, 1
	v_lshrrev_b32_e32 v3, 22, v3
	v_add_u32_e32 v3, v2, v3
	v_and_b32_e32 v3, 0xfffffc00, v3
	v_sub_u32_e32 v2, v2, v3
	v_lshrrev_b32_e32 v3, 4, v2
	v_ashrrev_i32_e32 v4, 31, v234
	v_bitop3_b32 v2, v3, v2, 32 bitop3:0x6c
	v_lshrrev_b32_e32 v4, 26, v4
	v_ashrrev_i32_e32 v3, 31, v2
	v_add_u32_e32 v4, v234, v4
	v_lshrrev_b32_e32 v3, 26, v3
	v_ashrrev_i32_e32 v15, 6, v4
	v_add_u32_e32 v3, v2, v3
	v_lshlrev_b32_e32 v4, 3, v15
	s_add_u32 s26, s0, 0x4980000
	v_ashrrev_i32_e32 v14, 6, v3
	v_and_b32_e32 v4, -16, v4
	s_addc_u32 s27, s1, 0
	v_add_u32_e32 v4, v14, v4
	v_and_b32_e32 v5, 3, v14
	s_ashr_i32 s29, s52, 31
	v_and_or_b32 v5, v4, s4, v5
	s_lshr_b32 s4, s29, 29
	s_add_i32 s4, s52, s4
	s_ashr_i32 s8, s5, 6
	s_ashr_i32 s6, s4, 3
	s_and_b32 s4, s4, -8
	s_ashr_i32 s9, s5, 8
	s_lshl_b32 s28, s8, 10
	s_sub_i32 s4, s52, s4
	s_cmp_lt_i32 s4, 0
	s_cselect_b32 s7, s49, 0x60
	s_mul_i32 s4, s4, s7
	s_add_i32 s4, s4, s6
	s_mul_hi_i32 s6, s4, 0x2aaaaaab
	s_lshr_b32 s7, s6, 31
	s_ashr_i32 s6, s6, 4
	s_add_i32 s6, s6, s7
	s_lshl_b32 s7, s6, 3
	s_mulk_i32 s6, 0x60
	s_sub_i32 s6, s4, s6
	s_bfe_i32 s4, s6, 0x80000
	s_bfe_u32 s4, s4, 0x3000c
	s_add_i32 s10, s6, s4
	s_bfe_i32 s4, s10, 0x80000
	s_and_b32 s10, s10, 0xf8
	s_sub_i32 s6, s6, s10
	s_sext_i32_i16 s4, s4
	s_sext_i32_i8 s6, s6
	v_lshrrev_b32_e32 v6, 2, v4
	v_lshlrev_b32_e32 v7, 1, v4
	v_and_b32_e32 v3, 0xc0, v3
	s_lshr_b32 s4, s4, 3
	s_add_i32 s18, s7, s6
	v_and_b32_e32 v6, 4, v6
	v_and_b32_e32 v7, 24, v7
	v_sub_u32_e32 v2, v2, v3
	s_ashr_i32 s19, s18, 31
	s_bfe_i64 s[10:11], s[4:5], 0x100000
	v_or3_b32 v5, v5, v6, v7
	v_lshlrev_b32_e32 v6, 5, v15
	v_ashrrev_i16_sdwa v2, v226, sext(v2) dst_sel:DWORD dst_unused:UNUSED_PAD src0_sel:DWORD src1_sel:BYTE_0
	s_lshl_b64 s[6:7], s[18:19], 19
	s_lshl_b64 s[10:11], s[10:11], 19
	v_and_b32_e32 v11, 15, v233
	v_and_b32_e32 v6, 32, v6
	v_bfe_i32 v16, v2, 0, 16
	s_add_u32 s20, s26, s10
	v_lshl_or_b32 v1, s9, 6, v11
	v_add_lshl_u32 v2, v6, v16, 1
	s_addc_u32 s21, s27, s11
	s_lshl_b32 s10, s18, 8
	v_lshl_add_u32 v134, v5, 11, v2
	v_lshl_add_u32 v136, v4, 11, v2
	v_add_u32_e32 v2, s10, v1
	v_or_b32_e32 v152, 16, v1
	v_or_b32_e32 v153, 32, v1
	v_or_b32_e32 v154, 48, v1
	v_add_u32_e32 v155, 0x80, v1
	v_add_u32_e32 v156, 0x90, v1
	v_add_u32_e32 v157, 0xa0, v1
	v_add_u32_e32 v158, 0xb0, v1
	v_ashrrev_i32_e32 v3, 31, v2
	v_add_u32_e32 v4, s10, v152
	v_add_u32_e32 v6, s10, v153
	v_add_u32_e32 v8, s10, v154
	v_add_u32_e32 v18, s10, v155
	v_add_u32_e32 v20, s10, v156
	v_add_u32_e32 v22, s10, v157
	v_add_u32_e32 v24, s10, v158
	s_add_i32 s30, s28, 0
	v_lshl_add_u64 v[2:3], v[2:3], 2, s[78:79]
	v_ashrrev_i32_e32 v5, 31, v4
	v_ashrrev_i32_e32 v7, 31, v6
	v_ashrrev_i32_e32 v9, 31, v8
	v_ashrrev_i32_e32 v19, 31, v18
	v_ashrrev_i32_e32 v21, 31, v20
	v_ashrrev_i32_e32 v23, 31, v22
	v_ashrrev_i32_e32 v25, 31, v24
	s_add_i32 m0, s30, 0x10000
	v_lshl_add_u64 v[4:5], v[4:5], 2, s[78:79]
	v_lshl_add_u64 v[6:7], v[6:7], 2, s[78:79]
	v_lshl_add_u64 v[8:9], v[8:9], 2, s[78:79]
	v_lshl_add_u64 v[18:19], v[18:19], 2, s[78:79]
	v_lshl_add_u64 v[20:21], v[20:21], 2, s[78:79]
	v_lshl_add_u64 v[22:23], v[22:23], 2, s[78:79]
	v_lshl_add_u64 v[24:25], v[24:25], 2, s[78:79]
	global_load_dword v149, v[2:3], off
	global_load_dword v148, v[4:5], off
	global_load_dword v147, v[6:7], off
	global_load_dword v146, v[8:9], off
	global_load_dword v145, v[18:19], off
	global_load_dword v143, v[20:21], off
	global_load_dword v142, v[22:23], off
	global_load_dword v144, v[24:25], off
	v_mov_b32_e32 v135, v0
	global_load_lds_dwordx4 v134, s[20:21]
	s_add_i32 m0, s30, 0x12000
	s_add_u32 s10, s20, 0x40000
	global_load_lds_dwordx4 v130, s[20:21]
	s_addc_u32 s11, s21, 0
	s_add_i32 m0, s30, 0x14000
	v_mov_b32_e32 v131, v0
	global_load_lds_dwordx4 v134, s[10:11]
	s_add_i32 m0, s30, 0x16000
	s_add_u32 s22, s80, s6
	s_addc_u32 s23, s81, s7
	s_add_i32 s31, s30, 0x2000
	global_load_lds_dwordx4 v130, s[10:11]
	s_mov_b32 m0, s30
	s_add_u32 s6, s22, 0x40000
	global_load_lds_dwordx4 v136, s[22:23]
	s_mov_b32 m0, s31
	s_addc_u32 s7, s23, 0
	s_add_i32 s34, s30, 0x4000
	global_load_lds_dwordx4 v132, s[22:23]
	s_mov_b32 m0, s34
	s_add_i32 s35, s30, 0x6000
	global_load_lds_dwordx4 v136, s[6:7]
	s_mov_b32 m0, s35
	v_mov_b32_e32 v137, v0
	global_load_lds_dwordx4 v132, s[6:7]
	v_mov_b32_e32 v133, v0
	s_cmp_eq_u32 s9, 1
	v_lshl_add_u64 v[8:9], s[20:21], 0, v[134:135]
	v_lshl_add_u64 v[6:7], s[20:21], 0, v[130:131]
	v_lshl_add_u64 v[2:3], s[22:23], 0, v[136:137]
	s_cselect_b64 s[6:7], -1, 0
	s_cmp_lg_u32 s9, 1
	v_lshl_add_u64 v[4:5], s[22:23], 0, v[132:133]
	s_cbranch_scc1 .Lprio0_3
	s_barrier
	s_branch .LBB0_634
